# latency stack on slab-barrier version: GLA-intra counted load waits, gla_inter epilogue loads issued behind main loads, P1 second table loop with 16 loads in flight
# speedup vs baseline: 1.0029x; 1.0015x over previous
; __device__ __forceinline__ void p1_rows(const Params& P, LAS unsigned char* lds, int G) {
;     ...
;     for (int idx = blockIdx.x * NTHREADS + tid; idx < 2 * NADA; idx += G * NTHREADS) { const int b = idx / NADA, n = idx % NADA; float v = P.b_ada[n];
;         for (int ks = 0; ks < KS_ADA; ++ks) v += adap[(size_t)(ks * 2 + b) * NADA + n];
;         ada[idx] = v; }
.LBB0_163:
	v_mul_hi_i32 v1, v0, s10
	v_lshrrev_b32_e32 v2, 31, v1
	v_ashrrev_i32_e32 v1, 11, v1
	v_add_u32_e32 v1, v1, v2
	v_mul_i32_i24_e32 v2, 0x3000, v1
	v_sub_u32_e32 v2, v0, v2
	v_ashrrev_i32_e32 v3, 31, v2
	v_lshlrev_b64 v[2:3], 2, v[2:3]
	v_lshl_add_u64 v[4:5], s[68:69], 0, v[2:3]
	global_load_dword v4, v[4:5], off
	v_mad_i64_i32 v[2:3], s[8:9], v1, s11, v[2:3]
	global_load_dword v14, v2, s[58:59]
	s_add_u32 s16, s58, 0x18000
	s_addc_u32 s17, s59, 0
	global_load_dword v15, v2, s[16:17]
	s_add_u32 s16, s58, 0x30000
	s_addc_u32 s17, s59, 0
	global_load_dword v16, v2, s[16:17]
	s_add_u32 s16, s58, 0x48000
	s_addc_u32 s17, s59, 0
	global_load_dword v17, v2, s[16:17]
	s_add_u32 s16, s58, 0x60000
	s_addc_u32 s17, s59, 0
	global_load_dword v18, v2, s[16:17]
	s_add_u32 s16, s58, 0x78000
	s_addc_u32 s17, s59, 0
	global_load_dword v19, v2, s[16:17]
	s_add_u32 s16, s58, 0x90000
	s_addc_u32 s17, s59, 0
	global_load_dword v20, v2, s[16:17]
	s_add_u32 s16, s58, 0xa8000
	s_addc_u32 s17, s59, 0
	global_load_dword v21, v2, s[16:17]
	s_add_u32 s16, s58, 0xc0000
	s_addc_u32 s17, s59, 0
	global_load_dword v22, v2, s[16:17]
	s_add_u32 s16, s58, 0xd8000
	s_addc_u32 s17, s59, 0
	global_load_dword v23, v2, s[16:17]
	s_add_u32 s16, s58, 0xf0000
	s_addc_u32 s17, s59, 0
	global_load_dword v24, v2, s[16:17]
	s_add_u32 s16, s58, 0x108000
	s_addc_u32 s17, s59, 0
	global_load_dword v25, v2, s[16:17]
	s_add_u32 s16, s58, 0x120000
	s_addc_u32 s17, s59, 0
	global_load_dword v26, v2, s[16:17]
	s_add_u32 s16, s58, 0x138000
	s_addc_u32 s17, s59, 0
	global_load_dword v27, v2, s[16:17]
	s_add_u32 s16, s58, 0x150000
	s_addc_u32 s17, s59, 0
	global_load_dword v28, v2, s[16:17]
	s_add_u32 s16, s58, 0x168000
	s_addc_u32 s17, s59, 0
	global_load_dword v29, v2, s[16:17]
	s_waitcnt vmcnt(15)
	v_add_f32_e32 v1, v4, v14
	s_waitcnt vmcnt(14)
	v_add_f32_e32 v1, v1, v15
	s_waitcnt vmcnt(13)
	v_add_f32_e32 v1, v1, v16
	s_waitcnt vmcnt(12)
	v_add_f32_e32 v1, v1, v17
	s_waitcnt vmcnt(11)
	v_add_f32_e32 v1, v1, v18
	s_waitcnt vmcnt(10)
	v_add_f32_e32 v1, v1, v19
	s_waitcnt vmcnt(9)
	v_add_f32_e32 v1, v1, v20
	s_waitcnt vmcnt(8)
	v_add_f32_e32 v1, v1, v21
	s_waitcnt vmcnt(7)
	v_add_f32_e32 v1, v1, v22
	s_waitcnt vmcnt(6)
	v_add_f32_e32 v1, v1, v23
	s_waitcnt vmcnt(5)
	v_add_f32_e32 v1, v1, v24
	s_waitcnt vmcnt(4)
	v_add_f32_e32 v1, v1, v25
	s_waitcnt vmcnt(3)
	v_add_f32_e32 v1, v1, v26
	s_waitcnt vmcnt(2)
	v_add_f32_e32 v1, v1, v27
	s_waitcnt vmcnt(1)
	v_add_f32_e32 v1, v1, v28
	s_waitcnt vmcnt(0)
	v_add_f32_e32 v4, v1, v29
	v_ashrrev_i32_e32 v1, 31, v0
	v_lshl_add_u64 v[2:3], v[0:1], 2, s[14:15]
	v_add_u32_e32 v0, s33, v0
	v_cmp_lt_i32_e32 vcc, s12, v0
	s_or_b64 s[6:7], vcc, s[6:7]
	global_store_dword v[2:3], v4, off
	s_andn2_b64 exec, exec, s[6:7]
	s_cbranch_execnz .LBB0_163

; #define MFMA16(a, b, c) __builtin_amdgcn_mfma_f32_16x16x32_bf16((a), (b), (c), 0, 0, 0)
; __device__ __forceinline__ void gla_inter_unit(const Params& P, LAS unsigned char* lds, int unit) {
;     ...
;     bf16x8 qf[4];
; #pragma unroll
;     for (int ks = 0; ks < 4; ++ks) qf[ks] = *(const bf16x8*)(qdec_g + ((size_t)unit * 64 + 16 * cb + fr) * 128 + 32 * ks + 8 * fq);
;     f32x4 o[8]; float ss = 0.f;
;     bf16x8 sf[8][4]; u32x2 oiw[8];
; #pragma unroll
;     for (int vbi = 0; vbi < 8; ++vbi) { const int vb = vh * 8 + vbi;
; #pragma unroll
;         for (int ks = 0; ks < 4; ++ks) sf[vbi][ks] = *(const bf16x8*)(ST + ((size_t)unit * 256 + 16 * vb + fr) * 128 + 32 * ks + 8 * fq);
;         oiw[vbi] = *(const u32x2*)(OI + trow * 1024 + 256 * h + 16 * vb + 4 * fq); }
; #pragma unroll
;     for (int vbi = 0; vbi < 8; ++vbi) { f32x4 acc = {0.f, 0.f, 0.f, 0.f};
; #pragma unroll
;         for (int ks = 0; ks < 4; ++ks) acc = MFMA16(sf[vbi][ks], qf[ks], acc);
;         const u32x2 w = oiw[vbi];
;         acc[0] += __uint_as_float(w.x << 16); acc[1] += __uint_as_float(w.x & 0xffff0000u); acc[2] += __uint_as_float(w.y << 16); acc[3] += __uint_as_float(w.y & 0xffff0000u);
.LBB0_543:
	v_mov_b32_e32 v54, v168
	v_mov_b32_e32 v3, v17
	v_ashrrev_i32_e32 v4, 1, v54
	v_and_b32_e32 v40, 0xffffff80, v4
	v_and_b32_e32 v152, 15, v54
	v_ashrrev_i32_e32 v41, 31, v40
	v_bfe_u32 v53, v54, 4, 2
	v_or_b32_e32 v6, v40, v152
	v_mov_b32_e32 v7, v41
	v_lshlrev_b32_e32 v2, 4, v53
	v_lshl_add_u64 v[6:7], s[38:39], 0, v[6:7]
	v_lshl_add_u64 v[4:5], s[0:1], 0, v[2:3]
	v_lshlrev_b64 v[6:7], 8, v[6:7]
	v_lshl_add_u64 v[38:39], v[4:5], 0, v[6:7]
	s_movk_i32 s22, 0xa000
	v_lshrrev_b32_e32 v0, 2, v54
	v_add_co_u32_e32 v4, vcc, s22, v38
	v_and_b32_e32 v55, 48, v0
	s_nop 0
	v_addc_co_u32_e32 v5, vcc, -1, v39, vcc
	v_or_b32_e32 v16, v55, v152
	global_load_dwordx4 v[18:21], v[4:5], off offset:-4096
	v_lshl_add_u64 v[0:1], s[52:53], 0, v[16:17]
	v_lshlrev_b64 v[0:1], 8, v[0:1]
	s_movk_i32 s22, 0xc000
	v_lshl_add_u64 v[0:1], s[36:37], 0, v[0:1]
	v_add_co_u32_e32 v80, vcc, s22, v38
	s_movk_i32 s22, 0x9000
	v_lshl_add_u64 v[12:13], v[0:1], 0, v[2:3]
	s_mov_b32 s23, -1
	global_load_dwordx4 v[0:3], v[12:13], off
	global_load_dwordx4 v[22:25], v[4:5], off
	v_lshl_add_u64 v[14:15], v[38:39], 0, s[22:23]
	s_movk_i32 s22, 0xa000
	s_mov_b32 s23, -1
	v_addc_co_u32_e32 v81, vcc, -1, v39, vcc
	v_lshl_add_u64 v[42:43], v[38:39], 0, s[22:23]
	global_load_dwordx4 v[26:29], v[80:81], off offset:-4096
	global_load_dwordx4 v[30:33], v[14:15], off offset:64
	global_load_dwordx4 v[4:7], v[12:13], off offset:64
	global_load_dwordx4 v[34:37], v[42:43], off offset:64
	s_movk_i32 s22, 0xb000
	s_mov_b32 s23, -1
	v_lshl_add_u64 v[76:77], v[38:39], 0, s[22:23]
	global_load_dwordx4 v[44:47], v[76:77], off offset:64
	global_load_dwordx4 v[56:59], v[14:15], off offset:128
	global_load_dwordx4 v[8:11], v[12:13], off offset:128
	global_load_dwordx4 v[60:63], v[42:43], off offset:128
	global_load_dwordx4 v[64:67], v[14:15], off offset:192
	s_nop 0
	global_load_dwordx4 v[12:15], v[12:13], off offset:192
	s_nop 0
	global_load_dwordx4 v[68:71], v[42:43], off offset:192
	global_load_dwordx4 v[72:75], v[76:77], off offset:128
	s_ashr_i32 s22, s27, 9
	global_load_dwordx4 v[80:83], v[80:81], off
	s_ashr_i32 s23, s22, 31
	global_load_dwordx4 v[76:79], v[76:77], off offset:192
	s_and_b32 s33, s52, 0x1fc0
	s_lshl_b64 s[22:23], s[22:23], 13
	s_or_b32 s22, s22, s33
	v_mov_b32_e32 v43, s23
	v_or_b32_e32 v42, s22, v16
	s_and_b32 s43, s3, 0x300
	v_lshlrev_b64 v[86:87], 11, v[42:43]
	s_movk_i32 s22, 0xc000
	s_lshl_b32 s68, s43, 1
	v_lshl_add_u64 v[86:87], s[28:29], 0, v[86:87]
	s_mov_b32 s23, -1
	v_mov_b32_e32 v85, v17
	v_lshlrev_b32_e32 v84, 3, v53
	v_lshl_add_u64 v[86:87], v[86:87], 0, s[68:69]
	v_lshl_add_u64 v[92:93], v[38:39], 0, s[22:23]
	v_lshl_add_u64 v[88:89], v[86:87], 0, v[84:85]
	global_load_dwordx4 v[84:87], v[92:93], off offset:64
	v_lshl_add_u64 v[136:137], v[40:41], 1, v[88:89]
	global_load_dwordx2 v[138:139], v[136:137], off
	global_load_dwordx4 v[88:91], v[92:93], off offset:128
	s_nop 0
	global_load_dwordx4 v[92:95], v[92:93], off offset:192
	s_movk_i32 s22, 0xe000
	v_add_co_u32_e32 v116, vcc, s22, v38
	s_movk_i32 s22, 0xd000
	s_nop 0
	v_addc_co_u32_e32 v117, vcc, -1, v39, vcc
	s_mov_b32 s23, -1
	global_load_dwordx4 v[96:99], v[116:117], off offset:-4096
	global_load_dwordx2 v[140:141], v[136:137], off offset:32
	v_lshl_add_u64 v[112:113], v[38:39], 0, s[22:23]
	global_load_dwordx4 v[100:103], v[112:113], off offset:64
	s_movk_i32 s22, 0xe000
	s_mov_b32 s23, -1
	v_lshl_add_u64 v[124:125], v[38:39], 0, s[22:23]
	global_load_dwordx4 v[104:107], v[112:113], off offset:128
	global_load_dwordx4 v[108:111], v[124:125], off offset:192
	global_load_dwordx2 v[142:143], v[136:137], off offset:64
	v_cmp_lt_i32_e32 vcc, v49, v50
	global_load_dwordx4 v[112:115], v[112:113], off offset:192
	s_waitcnt vmcnt(25)
	v_mfma_f32_16x16x32_bf16 v[22:25], v[22:25], v[0:3], 0
	global_load_dwordx4 v[116:119], v[116:117], off
	s_nop 0
	global_load_dwordx4 v[120:123], v[124:125], off offset:64
	global_load_dwordx2 v[144:145], v[136:137], off offset:96
	v_mfma_f32_16x16x32_bf16 v[18:21], v[18:21], v[0:3], 0
	global_load_dwordx4 v[124:127], v[124:125], off offset:128
	s_nop 0
	global_load_dwordx4 v[128:131], v[38:39], off offset:-4096
	global_load_dwordx2 v[146:147], v[136:137], off offset:128
	global_load_dwordx4 v[132:135], v[38:39], off offset:-4032
	s_waitcnt vmcnt(29)
	v_mfma_f32_16x16x32_bf16 v[18:21], v[30:33], v[4:7], v[18:21]
	s_waitcnt vmcnt(28)
	v_mfma_f32_16x16x32_bf16 v[22:25], v[34:37], v[4:7], v[22:25]
	s_waitcnt vmcnt(16)
; #define MFMA16(a, b, c) __builtin_amdgcn_mfma_f32_16x16x32_bf16((a), (b), (c), 0, 0, 0)
; __device__ __forceinline__ void gla_inter_unit(const Params& P, LAS unsigned char* lds, int unit) {
;     ...
;     for (int vbi = 0; vbi < 8; ++vbi) { f32x4 acc = {0.f, 0.f, 0.f, 0.f};
; #pragma unroll
;         for (int ks = 0; ks < 4; ++ks) acc = MFMA16(sf[vbi][ks], qf[ks], acc);
;         const u32x2 w = oiw[vbi];
;         acc[0] += __uint_as_float(w.x << 16); acc[1] += __uint_as_float(w.x & 0xffff0000u); acc[2] += __uint_as_float(w.y << 16); acc[3] += __uint_as_float(w.y & 0xffff0000u);
;         o[vbi] = acc; ss += (acc[0] * acc[0] + acc[1] * acc[1]) + (acc[2] * acc[2] + acc[3] * acc[3]); }
;     ...
;     for (int vbi = 0; vbi < 8; ++vbi) { const int vcol = 16 * (vh * 8 + vbi) + 4 * fq;
;         const f32x4 g = *(const f32x4*)(P.g_gla + vcol); const u32x2 rw = *(const u32x2*)(Z + trow * ZC + ZO_RG + 256 * h + vcol);
	v_lshlrev_b32_e32 v34, 16, v138
	v_mfma_f32_16x16x32_bf16 v[18:21], v[56:59], v[8:11], v[18:21]
	global_load_dwordx4 v[56:59], v[38:39], off offset:-3968
	global_load_dwordx2 v[148:149], v[136:137], off offset:160
	v_and_b32_e32 v35, 0xffff0000, v138
	v_mfma_f32_16x16x32_bf16 v[26:29], v[26:29], v[0:3], 0
	v_mfma_f32_16x16x32_bf16 v[22:25], v[60:63], v[8:11], v[22:25]
	global_load_dwordx4 v[60:63], v[38:39], off offset:-3904
	v_mfma_f32_16x16x32_bf16 v[18:21], v[64:67], v[12:15], v[18:21]
	global_load_dwordx4 v[64:67], v[38:39], off
	v_mfma_f32_16x16x32_bf16 v[26:29], v[44:47], v[4:7], v[26:29]
	v_mfma_f32_16x16x32_bf16 v[22:25], v[68:71], v[12:15], v[22:25]
	global_load_dwordx4 v[68:71], v[38:39], off offset:64
	global_load_dwordx2 v[150:151], v[136:137], off offset:192
	s_nop 2
	v_pk_add_f32 v[46:47], v[18:19], v[34:35]
	global_load_dwordx2 v[136:137], v[136:137], off offset:224
	v_mfma_f32_16x16x32_bf16 v[26:29], v[72:75], v[8:11], v[26:29]
	global_load_dwordx4 v[72:75], v[38:39], off offset:128
	v_lshlrev_b32_e32 v18, 16, v139
	v_and_b32_e32 v19, 0xffff0000, v139
	v_mfma_f32_16x16x32_bf16 v[26:29], v[76:79], v[12:15], v[26:29]
	global_load_dwordx4 v[76:79], v[38:39], off offset:192
	v_bfe_u32 v153, v168, 4, 2
	v_ashrrev_i32_e32 v154, 1, v168
	v_and_b32_e32 v154, 0xffffff80, v154
	v_lshl_or_b32 v156, v153, 2, v154
	v_ashrrev_i32_e32 v157, 31, v156
	v_lshrrev_b32_e32 v155, 2, v168
	v_and_b32_e32 v155, 48, v155
	v_and_or_b32 v155, v168, 15, v155
	s_ashr_i32 s8, s27, 9
	s_ashr_i32 s9, s8, 31
	s_lshl_b64 s[8:9], s[8:9], 13
	s_and_b32 s6, s52, 0x1fc0
	s_or_b32 s8, s8, s6
	v_or_b32_e32 v158, s8, v155
	v_mov_b32_e32 v159, s9
	v_lshlrev_b64 v[158:159], 13, v[158:159]
	v_lshl_add_u64 v[158:159], s[56:57], 0, v[158:159]
	s_and_b32 s8, s3, 0x300
	s_lshl_b32 s8, s8, 1
	s_mov_b32 s9, 0
	v_lshl_add_u64 v[158:159], v[158:159], 0, s[8:9]
	v_lshl_add_u64 v[158:159], v[156:157], 1, v[158:159]
	s_mov_b64 s[8:9], 0x1600
	v_lshl_add_u64 v[158:159], v[158:159], 0, s[8:9]
	v_lshl_add_u64 v[160:161], v[156:157], 2, s[90:91]
	global_load_dwordx4 v[176:179], v[160:161], off
	global_load_dwordx2 v[210:211], v[158:159], off
	global_load_dwordx4 v[180:183], v[160:161], off offset:64
	global_load_dwordx2 v[212:213], v[158:159], off offset:32
	global_load_dwordx4 v[184:187], v[160:161], off offset:128
	global_load_dwordx2 v[214:215], v[158:159], off offset:64
	global_load_dwordx4 v[188:191], v[160:161], off offset:192
	global_load_dwordx2 v[216:217], v[158:159], off offset:96
	global_load_dwordx4 v[192:195], v[160:161], off offset:256
	global_load_dwordx2 v[218:219], v[158:159], off offset:128
	global_load_dwordx4 v[196:199], v[160:161], off offset:320
	global_load_dwordx2 v[220:221], v[158:159], off offset:160
	global_load_dwordx4 v[200:203], v[160:161], off offset:384
	global_load_dwordx2 v[222:223], v[158:159], off offset:192
	global_load_dwordx4 v[204:207], v[160:161], off offset:448
	global_load_dwordx2 v[224:225], v[158:159], off offset:224
	v_pk_add_f32 v[44:45], v[20:21], v[18:19]
	v_mfma_f32_16x16x32_bf16 v[30:33], v[80:83], v[0:3], 0
	v_mfma_f32_16x16x32_bf16 v[30:33], v[84:87], v[4:7], v[30:33]
	v_mul_f32_e64 v84, v46, v46
	v_mul_f32_e64 v85, v47, v47
	v_pk_mul_f32 v[86:87], v[44:45], v[44:45]
	s_waitcnt vmcnt(40)
	v_mfma_f32_16x16x32_bf16 v[30:33], v[88:91], v[8:11], v[30:33]
	v_add_f32_e32 v16, v86, v87
	s_waitcnt vmcnt(39)
	v_mfma_f32_16x16x32_bf16 v[18:21], v[92:95], v[12:15], v[30:33]
	s_waitcnt vmcnt(37)
	s_nop 3
	v_lshlrev_b32_e32 v30, 16, v140
	v_and_b32_e32 v31, 0xffff0000, v140
	v_pk_add_f32 v[38:39], v[22:23], v[30:31]
	v_mfma_f32_16x16x32_bf16 v[30:33], v[96:99], v[0:3], 0
	v_lshlrev_b32_e32 v22, 16, v141
	v_and_b32_e32 v23, 0xffff0000, v141
	v_pk_add_f32 v[36:37], v[24:25], v[22:23]
	s_waitcnt vmcnt(36)
	v_mfma_f32_16x16x32_bf16 v[22:25], v[100:103], v[4:7], v[30:33]
	v_mul_f32_e64 v88, v38, v38
	v_mul_f32_e64 v89, v39, v39
	v_pk_mul_f32 v[90:91], v[36:37], v[36:37]
	s_waitcnt vmcnt(33)
	v_lshlrev_b32_e32 v30, 16, v142
	v_and_b32_e32 v31, 0xffff0000, v142
	v_pk_add_f32 v[34:35], v[26:27], v[30:31]
	v_lshlrev_b32_e32 v26, 16, v143
	v_and_b32_e32 v27, 0xffff0000, v143
	v_pk_add_f32 v[32:33], v[28:29], v[26:27]
	s_waitcnt vmcnt(31)
; #define MFMA16(a, b, c) __builtin_amdgcn_mfma_f32_16x16x32_bf16((a), (b), (c), 0, 0, 0)
; __device__ __forceinline__ void gla_inter_unit(const Params& P, LAS unsigned char* lds, int unit) {
;     ...
;     for (int vbi = 0; vbi < 8; ++vbi) { f32x4 acc = {0.f, 0.f, 0.f, 0.f};
; #pragma unroll
;         for (int ks = 0; ks < 4; ++ks) acc = MFMA16(sf[vbi][ks], qf[ks], acc);
;         const u32x2 w = oiw[vbi];
;         acc[0] += __uint_as_float(w.x << 16); acc[1] += __uint_as_float(w.x & 0xffff0000u); acc[2] += __uint_as_float(w.y << 16); acc[3] += __uint_as_float(w.y & 0xffff0000u);
;         o[vbi] = acc; ss += (acc[0] * acc[0] + acc[1] * acc[1]) + (acc[2] * acc[2] + acc[3] * acc[3]); }
;     ss += __shfl_xor(ss, 16); ss += __shfl_xor(ss, 32);
;     if (fq == 0) red[wid * 16 + fr] = ss;
	v_mfma_f32_16x16x32_bf16 v[26:29], v[116:119], v[0:3], 0
	s_waitcnt vmcnt(29)
	v_lshlrev_b32_e32 v30, 16, v144
	v_and_b32_e32 v31, 0xffff0000, v144
	v_pk_add_f32 v[30:31], v[18:19], v[30:31]
	v_mfma_f32_16x16x32_bf16 v[26:29], v[120:123], v[4:7], v[26:29]
	v_lshlrev_b32_e32 v18, 16, v145
	v_and_b32_e32 v19, 0xffff0000, v145
	v_pk_mul_f32 v[92:93], v[34:35], v[34:35]
	s_waitcnt vmcnt(28)
	v_mfma_f32_16x16x32_bf16 v[80:83], v[124:127], v[8:11], v[26:29]
	v_mul_f32_e64 v94, v32, v32
	v_mul_f32_e64 v95, v33, v33
	v_pk_mul_f32 v[96:97], v[30:31], v[30:31]
	v_pk_add_f32 v[28:29], v[20:21], v[18:19]
	v_mfma_f32_16x16x32_bf16 v[18:21], v[108:111], v[12:15], v[80:83]
	s_waitcnt vmcnt(26)
	v_lshlrev_b32_e32 v26, 16, v146
	v_and_b32_e32 v27, 0xffff0000, v146
	v_pk_mul_f32 v[98:99], v[28:29], v[28:29]
	v_mfma_f32_16x16x32_bf16 v[80:83], v[128:131], v[0:3], 0
	s_waitcnt vmcnt(25)
	v_mfma_f32_16x16x32_bf16 v[80:83], v[132:135], v[4:7], v[80:83]
	s_waitcnt vmcnt(21)
	v_mfma_f32_16x16x32_bf16 v[0:3], v[64:67], v[0:3], 0
	v_mfma_f32_16x16x32_bf16 v[56:59], v[56:59], v[8:11], v[80:83]
	s_waitcnt vmcnt(20)
	v_mfma_f32_16x16x32_bf16 v[0:3], v[68:71], v[4:7], v[0:3]
	s_waitcnt vmcnt(19)
	v_lshlrev_b32_e32 v4, 16, v151
	v_and_b32_e32 v5, 0xffff0000, v151
	v_mfma_f32_16x16x32_bf16 v[22:25], v[104:107], v[8:11], v[22:25]
	v_mfma_f32_16x16x32_bf16 v[56:59], v[60:63], v[12:15], v[56:59]
	s_waitcnt vmcnt(17)
	v_mfma_f32_16x16x32_bf16 v[0:3], v[72:75], v[8:11], v[0:3]
	v_mfma_f32_16x16x32_bf16 v[22:25], v[112:115], v[12:15], v[22:25]
	s_nop 4
	v_add_f32_e64 v6, v58, v4
	v_add_f32_e64 v7, v59, v5
	v_pk_mul_f32 v[10:11], v[6:7], v[6:7]
	s_waitcnt vmcnt(16)
	v_mfma_f32_16x16x32_bf16 v[2:5], v[76:79], v[12:15], v[0:3]
	v_add_f32_e32 v14, v88, v89
	v_add_f32_e32 v15, v90, v91
	v_add_f32_e32 v14, v14, v15
	v_add_f32_e32 v15, v84, v85
	v_add_f32_e32 v15, v15, v16
	v_add_f32_e32 v14, v15, v14
	v_add_f32_e32 v15, v92, v93
	v_add_f32_e32 v16, v94, v95
	v_pk_add_f32 v[26:27], v[22:23], v[26:27]
	v_lshlrev_b32_e32 v22, 16, v147
	v_and_b32_e32 v23, 0xffff0000, v147
	v_add_f32_e32 v15, v15, v16
	v_pk_add_f32 v[24:25], v[24:25], v[22:23]
	v_lshlrev_b32_e32 v22, 16, v148
	v_and_b32_e32 v23, 0xffff0000, v148
	v_add_f32_e32 v14, v14, v15
	v_add_f32_e32 v15, v96, v97
	v_add_f32_e32 v16, v98, v99
	v_pk_mul_f32 v[100:101], v[26:27], v[26:27]
	v_pk_mul_f32 v[102:103], v[24:25], v[24:25]
	v_pk_add_f32 v[22:23], v[18:19], v[22:23]
	v_lshlrev_b32_e32 v18, 16, v149
	v_and_b32_e32 v19, 0xffff0000, v149
	v_add_f32_e32 v15, v15, v16
	v_pk_add_f32 v[20:21], v[20:21], v[18:19]
	v_lshlrev_b32_e32 v18, 16, v150
	v_and_b32_e32 v19, 0xffff0000, v150
	v_lshlrev_b32_e32 v0, 16, v136
	v_and_b32_e32 v1, 0xffff0000, v136
	v_add_f32_e32 v14, v14, v15
	v_add_f32_e32 v15, v100, v101
	v_add_f32_e32 v16, v102, v103
	v_pk_mul_f32 v[60:61], v[22:23], v[22:23]
	v_pk_mul_f32 v[62:63], v[20:21], v[20:21]
	v_pk_add_f32 v[18:19], v[56:57], v[18:19]
	v_pk_add_f32 v[2:3], v[2:3], v[0:1]
	v_lshlrev_b32_e32 v0, 16, v137
	v_and_b32_e32 v1, 0xffff0000, v137
	v_add_f32_e32 v15, v15, v16
	v_pk_mul_f32 v[8:9], v[18:19], v[18:19]
	v_pk_add_f32 v[0:1], v[4:5], v[0:1]
	v_add_f32_e32 v14, v14, v15
	v_add_f32_e32 v15, v60, v61
	v_add_f32_e32 v16, v62, v63
	v_pk_mul_f32 v[4:5], v[2:3], v[2:3]
	v_pk_mul_f32 v[12:13], v[0:1], v[0:1]
	v_add_f32_e32 v15, v15, v16
	v_add_f32_e32 v10, v10, v11
	v_add_f32_e32 v8, v8, v9
	v_add_f32_e32 v14, v14, v15
	v_add_f32_e32 v8, v8, v10
	v_add_f32_e32 v9, v12, v13
	v_add_f32_e32 v4, v4, v5
	v_add_f32_e32 v8, v14, v8
	v_add_f32_e32 v4, v4, v9
	v_cndmask_b32_e32 v5, v48, v49, vcc
	v_add_f32_e32 v4, v8, v4
	v_lshlrev_b32_e32 v5, 2, v5
	ds_bpermute_b32 v5, v5, v4
	v_cmp_lt_i32_e32 vcc, v51, v50
	s_waitcnt lgkmcnt(0)
	v_add_f32_e32 v5, v4, v5
	v_cndmask_b32_e32 v4, v48, v51, vcc
	v_lshlrev_b32_e32 v4, 2, v4
	ds_bpermute_b32 v8, v4, v5
	v_cmp_eq_u32_e32 vcc, 0, v53
	v_lshlrev_b32_e32 v4, 2, v152
	s_and_saveexec_b64 s[22:23], vcc
	s_cbranch_execz .LBB0_542
	s_waitcnt lgkmcnt(0)
	v_add_f32_e32 v5, v5, v8
	v_and_b32_e32 v8, 0xffffffc0, v54
	v_add3_u32 v8, 0, v8, v4
	ds_write_b32 v8, v5
	s_branch .LBB0_542
